# attention: fold peeled iter into loop, mid-iteration barrier, waves4-7 staggered half iteration
# speedup vs baseline: 1.0186x; 1.0186x over previous
; #define LAS __attribute__((address_space(3)))
; DI void attn_unit(LAS unsigned char* lds, const bf16_t* Q, const bf16_t* Kn, const bf16_t* Kpe, const bf16_t* Vt, bf16_t* O, int b, int h, int qb) {
;     ...
;     f32x16 o[2][2];
; #pragma unroll
;     for (int j = 0; j < 2; ++j)
; #pragma unroll
;         for (int i = 0; i < 16; ++i) { o[j][0][i] = 0.f; o[j][1][i] = 0.f; }
;     float mrun[2] = {0.f, 0.f}, lsum[2] = {0.f, 0.f};
;     __syncthreads();
;     *(LAS u32x4*)(Ks + kn_l) = rk; if (tid < 256) *(LAS u32x4*)(Ks + kp_l) = rp;
;     *(LAS u32x2*)(Vs + vt_l) = (u32x2){rv.x, rv.y}; *(LAS u32x2*)(Vs + vt_l + 8) = (u32x2){rv.z, rv.w};
;     __syncthreads();
;     for (int kt = 0; kt < 64; ++kt) {
;         const int buf = kt & 1;
;         LAS unsigned char* kb = Ks + buf * KBUF; LAS unsigned char* vb = Vs + buf * VBUF;
;         f32x16 s[2][2];
; #pragma unroll
;         for (int j = 0; j < 2; ++j) { const float negm = -mrun[j];
; #pragma unroll
;             for (int i = 0; i < 16; ++i) { s[j][0][i] = negm; s[j][1][i] = negm; } }
;         if (wid < 4) __builtin_amdgcn_s_setprio(3); else __builtin_amdgcn_s_setprio(1);
; #pragma unroll
;         for (int t = 0; t < 6; ++t) {
;             const bf16x8 ka0 = *(const LAS bf16x8*)(kb + r32 * KPITCH + (16 * t + 8 * hi) * 2);
;             const bf16x8 ka1 = *(const LAS bf16x8*)(kb + (32 + r32) * KPITCH + (16 * t + 8 * hi) * 2);
; #pragma unroll
;             for (int j = 0; j < 2; ++j) {
;                 s[j][0] = __builtin_amdgcn_mfma_f32_32x32x16_bf16(ka0, qf[j][t], s[j][0], 0, 0, 0);
;                 s[j][1] = __builtin_amdgcn_mfma_f32_32x32x16_bf16(ka1, qf[j][t], s[j][1], 0, 0, 0);
;             }
;         }
;         __builtin_amdgcn_s_setprio(0);
;         __builtin_amdgcn_sched_barrier(0);
.LBB0_1118:
	s_or_b64 exec, exec, s[6:7]
	s_movk_i32 s6, 0x88
	v_mul_lo_u32 v4, v9, s6
	v_add3_u32 v211, 0, v4, v8
	s_cmpk_gt_i32 s2, 0xff
	v_add_u32_e32 v4, 0x6800, v211
	s_cselect_b64 s[26:27], -1, 0
	s_cmpk_lt_i32 s2, 0x100
	s_mov_b64 s[6:7], -1
	s_waitcnt vmcnt(0)
	ds_write2_b64 v4, v[0:1], v[2:3] offset1:1
	s_waitcnt lgkmcnt(0)
	s_barrier
	v_mov_b32_e32 v250, 0x700
	s_mov_b32 s19, 0x800000
	v_readlane_b32 s42, v254, 58
	v_readlane_b32 s43, v254, 59
	s_movk_i32 s0, 0xd0
	v_mad_u32_u24 v227, v226, s0, 0
	v_lshl_add_u32 v239, v68, 4, v227
	v_add_u32_e32 v243, 0x1000, v64
	v_add_u32_e32 v242, v223, v224
	v_add3_u32 v216, v220, v219, 64
	v_add_u32_e32 v188, 0x1000, v188
	v_mul_i32_i24_e32 v32, 0xffffffb8, v226
	v_lshlrev_b32_e32 v33, 3, v68
	v_add3_u32 v241, v227, v32, v33
	v_and_b32_e32 v65, 64, v233
	v_xor_b32_e32 v64, 32, v233
	v_add_u32_e32 v65, 64, v65
	v_cmp_lt_i32_e32 vcc, v64, v65
	s_nop 1
	v_cndmask_b32_e32 v64, v233, v64, vcc
	v_lshlrev_b32_e32 v240, 2, v64
	v_mov_b32_e32 v0, 0
	v_mov_b32_e32 v1, 0
	v_mov_b32_e32 v2, 0
	v_mov_b32_e32 v3, 0
	v_mov_b32_e32 v4, 0
	v_mov_b32_e32 v5, 0
	v_mov_b32_e32 v6, 0
	v_mov_b32_e32 v7, 0
	v_mov_b32_e32 v8, 0
	v_mov_b32_e32 v9, 0
	v_mov_b32_e32 v10, 0
	v_mov_b32_e32 v11, 0
	v_mov_b32_e32 v12, 0
	v_mov_b32_e32 v13, 0
	v_mov_b32_e32 v14, 0
	v_mov_b32_e32 v15, 0
	v_mov_b32_e32 v16, 0
	v_mov_b32_e32 v17, 0
	v_mov_b32_e32 v18, 0
	v_mov_b32_e32 v19, 0
	v_mov_b32_e32 v20, 0
	v_mov_b32_e32 v21, 0
	v_mov_b32_e32 v22, 0
	v_mov_b32_e32 v23, 0
	v_mov_b32_e32 v24, 0
	v_mov_b32_e32 v25, 0
	v_mov_b32_e32 v26, 0
	v_mov_b32_e32 v27, 0
	v_mov_b32_e32 v28, 0
	v_mov_b32_e32 v29, 0
	v_mov_b32_e32 v30, 0
	v_mov_b32_e32 v31, 0
	v_mov_b32_e32 v32, 0
	v_mov_b32_e32 v33, 0
	v_mov_b32_e32 v34, 0
	v_mov_b32_e32 v35, 0
	v_mov_b32_e32 v36, 0
	v_mov_b32_e32 v37, 0
	v_mov_b32_e32 v38, 0
	v_mov_b32_e32 v39, 0
	v_mov_b32_e32 v40, 0
	v_mov_b32_e32 v41, 0
	v_mov_b32_e32 v42, 0
	v_mov_b32_e32 v43, 0
	v_mov_b32_e32 v44, 0
	v_mov_b32_e32 v45, 0
	v_mov_b32_e32 v46, 0
	v_mov_b32_e32 v47, 0
	v_mov_b32_e32 v48, 0
	v_mov_b32_e32 v49, 0
	v_mov_b32_e32 v50, 0
	v_mov_b32_e32 v51, 0
	v_mov_b32_e32 v52, 0
	v_mov_b32_e32 v53, 0
	v_mov_b32_e32 v54, 0
	v_mov_b32_e32 v55, 0
	v_mov_b32_e32 v56, 0
	v_mov_b32_e32 v57, 0
	v_mov_b32_e32 v58, 0
	v_mov_b32_e32 v59, 0
	v_mov_b32_e32 v60, 0
	v_mov_b32_e32 v61, 0
	v_mov_b32_e32 v62, 0
	v_mov_b32_e32 v63, 0
	v_mov_b32_e32 v212, 0
	v_mov_b32_e32 v213, 0
	v_mov_b32_e32 v214, 0
	v_mov_b32_e32 v215, 0
	s_mov_b32 s28, 0
	s_mov_b32 s29, 0xfffff800
	s_mov_b32 s100, 0xff800000
	s_and_b64 vcc, exec, s[26:27]
	s_cbranch_vccz .Lat_loop
	v_mov_b32_e32 v217, v189
	v_lshl_add_u64 v[180:181], v[188:189], 1, s[20:21]
	v_lshl_add_u64 v[184:185], v[216:217], 1, s[24:25]
	global_load_dwordx4 v[180:183], v[180:181], off
	s_nop 0
	global_load_dwordx4 v[184:187], v[184:185], off
	s_barrier
.Lat_loop:
	s_and_b64 vcc, exec, s[26:27]
	s_cbranch_vccnz .Lat_p1b
	s_setprio 3
	s_branch .Lat_h1
.Lat_p1b:
	s_setprio 1
.Lat_h1:
	s_and_b32 s30, s28, 1
	s_mul_i32 s2, s30, 0x3400
	v_add_u32_e32 v217, s2, v239
	ds_read_b128 v[218:221], v217
	ds_read_b128 v[222:225], v217 offset:6656
	v_xor_b32_e32 v64, 0x80000000, v215
	v_xor_b32_e32 v80, 0x80000000, v214
	v_mov_b32_e32 v65, v64
	v_mov_b32_e32 v66, v64
	v_mov_b32_e32 v67, v64
	v_mov_b32_e32 v68, v64
	v_mov_b32_e32 v69, v64
	v_mov_b32_e32 v70, v64
	v_mov_b32_e32 v71, v64
	v_mov_b32_e32 v72, v64
	v_mov_b32_e32 v73, v64
	v_mov_b32_e32 v74, v64
	v_mov_b32_e32 v75, v64
	v_mov_b32_e32 v76, v64
	v_mov_b32_e32 v77, v64
	v_mov_b32_e32 v78, v64
	v_mov_b32_e32 v79, v64
	v_mov_b32_e32 v81, v80
	v_mov_b32_e32 v82, v80
	v_mov_b32_e32 v83, v80
	v_mov_b32_e32 v84, v80
	v_mov_b32_e32 v85, v80
	v_mov_b32_e32 v86, v80
	v_mov_b32_e32 v87, v80
	v_mov_b32_e32 v88, v80
	v_mov_b32_e32 v89, v80
	v_mov_b32_e32 v90, v80
	v_mov_b32_e32 v91, v80
	v_mov_b32_e32 v92, v80
	v_mov_b32_e32 v93, v80
	v_mov_b32_e32 v94, v80
	v_mov_b32_e32 v95, v80
	s_waitcnt lgkmcnt(1)
	v_mfma_f32_32x32x16_bf16 v[112:127], v[218:221], v[172:175], v[64:79]
	s_waitcnt lgkmcnt(0)
	v_mfma_f32_32x32x16_bf16 v[64:79], v[222:225], v[172:175], v[64:79]
	v_mfma_f32_32x32x16_bf16 v[96:111], v[218:221], v[148:151], v[80:95]
	ds_read_b128 v[218:221], v217 offset:32
	v_mfma_f32_32x32x16_bf16 v[80:95], v[222:225], v[148:151], v[80:95]
	ds_read_b128 v[222:225], v217 offset:6688
	s_waitcnt lgkmcnt(1)
	v_mfma_f32_32x32x16_bf16 v[112:127], v[218:221], v[128:131], v[112:127]
	s_waitcnt lgkmcnt(0)
	v_mfma_f32_32x32x16_bf16 v[64:79], v[222:225], v[128:131], v[64:79]
	v_mfma_f32_32x32x16_bf16 v[96:111], v[218:221], v[152:155], v[96:111]
	ds_read_b128 v[218:221], v217 offset:64
	v_mfma_f32_32x32x16_bf16 v[80:95], v[222:225], v[152:155], v[80:95]
	ds_read_b128 v[222:225], v217 offset:6720
	s_waitcnt lgkmcnt(1)
	v_mfma_f32_32x32x16_bf16 v[112:127], v[218:221], v[132:135], v[112:127]
	s_waitcnt lgkmcnt(0)
	v_mfma_f32_32x32x16_bf16 v[64:79], v[222:225], v[132:135], v[64:79]
	v_mfma_f32_32x32x16_bf16 v[96:111], v[218:221], v[156:159], v[96:111]
	ds_read_b128 v[218:221], v217 offset:96
	v_mfma_f32_32x32x16_bf16 v[80:95], v[222:225], v[156:159], v[80:95]
	ds_read_b128 v[222:225], v217 offset:6752
	s_waitcnt lgkmcnt(1)
	v_mfma_f32_32x32x16_bf16 v[112:127], v[218:221], v[136:139], v[112:127]
	s_waitcnt lgkmcnt(0)
	v_mfma_f32_32x32x16_bf16 v[64:79], v[222:225], v[136:139], v[64:79]
	v_mfma_f32_32x32x16_bf16 v[96:111], v[218:221], v[160:163], v[96:111]
	ds_read_b128 v[218:221], v217 offset:128
	v_mfma_f32_32x32x16_bf16 v[80:95], v[222:225], v[160:163], v[80:95]
	ds_read_b128 v[222:225], v217 offset:6784
	s_waitcnt lgkmcnt(1)
	v_mfma_f32_32x32x16_bf16 v[112:127], v[218:221], v[140:143], v[112:127]
	s_waitcnt lgkmcnt(0)
	v_mfma_f32_32x32x16_bf16 v[64:79], v[222:225], v[140:143], v[64:79]
	v_mfma_f32_32x32x16_bf16 v[96:111], v[218:221], v[164:167], v[96:111]
	ds_read_b128 v[218:221], v217 offset:160
	v_mfma_f32_32x32x16_bf16 v[80:95], v[222:225], v[164:167], v[80:95]
	ds_read_b128 v[222:225], v217 offset:6816
	s_waitcnt lgkmcnt(1)
	v_mfma_f32_32x32x16_bf16 v[112:127], v[218:221], v[144:147], v[112:127]
	s_waitcnt lgkmcnt(0)
	v_mfma_f32_32x32x16_bf16 v[64:79], v[222:225], v[144:147], v[64:79]
	v_mfma_f32_32x32x16_bf16 v[96:111], v[218:221], v[168:171], v[96:111]
	v_mfma_f32_32x32x16_bf16 v[80:95], v[222:225], v[168:171], v[80:95]
	s_setprio 0
	s_cmp_lg_u32 s29, 0x1f000
	s_cselect_b64 s[16:17], -1, 0
	s_cbranch_scc0 .Lat_mid
	s_and_b64 vcc, exec, s[26:27]
	s_cbranch_vccnz .Lat_h1b
	v_mov_b32_e32 v217, v189
	v_lshl_add_u64 v[180:181], v[188:189], 1, s[20:21]
	v_lshl_add_u64 v[184:185], v[216:217], 1, s[24:25]
	global_load_dwordx4 v[180:183], v[180:181], off
	s_nop 0
	global_load_dwordx4 v[184:187], v[184:185], off
	v_add_u32_e32 v176, s29, v243
	v_mov_b32_e32 v177, v189
	v_lshl_add_u64 v[176:177], v[176:177], 1, s[22:23]
	global_load_dwordx4 v[176:179], v[176:177], off
	s_branch .Lat_mid
; #define LAS __attribute__((address_space(3)))
; DI void attn_unit(LAS unsigned char* lds, const bf16_t* Q, const bf16_t* Kn, const bf16_t* Kpe, const bf16_t* Vt, bf16_t* O, int b, int h, int qb) {
;     ...
;         if (kt + 1 < 64) {
;             rk = *(const u32x4*)(kn_b + (kn_o + (unsigned)(kt + 1) * 4096u)); rv = *(const u32x4*)(vt_b + (vt_o + (unsigned)(kt + 1) * 64u));
;             if (tid < 256) rp = *(const u32x4*)(kp_b + (kp_o + (unsigned)(kt + 1) * 2048u));
;         }
;         __builtin_amdgcn_sched_barrier(0);
;         float mx[2];
; #pragma unroll
;         for (int j = 0; j < 2; ++j) {
;             mx[j] = fmaxf(s[j][0][0], s[j][1][0]);
; #pragma unroll
;             for (int i = 1; i < 16; ++i) mx[j] = fmaxf(mx[j], fmaxf(s[j][0][i], s[j][1][i]));
;         }
;         { const float o0 = __shfl_xor(mx[0], 32), o1 = __shfl_xor(mx[1], 32); mx[0] = fmaxf(mx[0], o0); mx[1] = fmaxf(mx[1], o1); }
;         if (kt == 0 || __builtin_amdgcn_ballot_w64(fmaxf(mx[0], mx[1]) > 6.0f) != 0ull) {
;     ...
;             LAS unsigned char* kn2 = Ks + (buf ^ 1) * KBUF; LAS unsigned char* vn2 = Vs + (buf ^ 1) * VBUF;
;             *(LAS u32x4*)(kn2 + kn_l) = rk; if (tid < 256) *(LAS u32x4*)(kn2 + kp_l) = rp;
;             *(LAS u32x2*)(vn2 + vt_l) = (u32x2){rv.x, rv.y}; *(LAS u32x2*)(vn2 + vt_l + 8) = (u32x2){rv.z, rv.w};
.Lat_h1b:
	s_xor_b32 s2, s30, 1
	s_mul_i32 s6, s2, 0x3400
	v_add_u32_e32 v217, s6, v210
	s_waitcnt vmcnt(1)
	ds_write_b128 v217, v[180:183]
	s_mulk_i32 s2, 0x2200
	v_add_u32_e32 v217, s2, v211
	v_add_u32_e32 v217, 0x6800, v217
	s_waitcnt vmcnt(0)
	ds_write2_b64 v217, v[184:185], v[186:187] offset1:1
.Lat_mid:
	s_waitcnt lgkmcnt(0)
	s_barrier
	s_and_b64 vcc, exec, s[26:27]
	s_cbranch_vccz .Lat_max
	s_cmp_lt_i32 s29, 0x1e800
	s_cbranch_scc0 .Lat_max
	v_add_u32_e32 v180, 0x1000, v188
	v_mov_b32_e32 v181, v189
	v_mov_b32_e32 v217, v189
	v_lshl_add_u64 v[180:181], v[180:181], 1, s[20:21]
	v_lshl_add_u64 v[184:185], v[216:217], 1, s[24:25]
	global_load_dwordx4 v[180:183], v[180:181], off
	s_nop 0
	global_load_dwordx4 v[184:187], v[184:185], off offset:128
.Lat_max:
	v_max_f32_e32 v217, v65, v65
	v_max_f32_e32 v218, v113, v113
	v_max_f32_e32 v217, v218, v217
	v_max_f32_e32 v218, v66, v66
	v_max_f32_e32 v219, v114, v114
	v_max_f32_e32 v218, v219, v218
	v_max_f32_e32 v219, v67, v67
	v_max_f32_e32 v220, v115, v115
	v_max3_f32 v217, v112, v64, v217
	v_max_f32_e32 v219, v220, v219
	v_max3_f32 v217, v217, v218, v219
	v_max_f32_e32 v218, v68, v68
	v_max_f32_e32 v219, v116, v116
	v_max_f32_e32 v218, v219, v218
	v_max_f32_e32 v219, v69, v69
	v_max_f32_e32 v220, v117, v117
	v_max_f32_e32 v219, v220, v219
	v_max3_f32 v217, v217, v218, v219
	v_max_f32_e32 v218, v70, v70
	v_max_f32_e32 v219, v118, v118
	v_max_f32_e32 v218, v219, v218
	v_max_f32_e32 v219, v71, v71
	v_max_f32_e32 v220, v119, v119
	v_max_f32_e32 v219, v220, v219
	v_max3_f32 v217, v217, v218, v219
	v_max_f32_e32 v218, v72, v72
	v_max_f32_e32 v219, v120, v120
	v_max_f32_e32 v218, v219, v218
	v_max_f32_e32 v219, v73, v73
	v_max_f32_e32 v220, v121, v121
	v_max_f32_e32 v219, v220, v219
	v_max3_f32 v217, v217, v218, v219
	v_max_f32_e32 v218, v74, v74
	v_max_f32_e32 v219, v122, v122
	v_max_f32_e32 v218, v219, v218
	v_max_f32_e32 v219, v75, v75
	v_max_f32_e32 v220, v123, v123
	v_max_f32_e32 v219, v220, v219
	v_max3_f32 v217, v217, v218, v219
	v_max_f32_e32 v218, v76, v76
	v_max_f32_e32 v219, v124, v124
	v_max_f32_e32 v218, v219, v218
	v_max_f32_e32 v219, v77, v77
	v_max_f32_e32 v220, v125, v125
	v_max_f32_e32 v219, v220, v219
	v_max3_f32 v217, v217, v218, v219
	v_max_f32_e32 v218, v78, v78
	v_max_f32_e32 v219, v126, v126
	v_max_f32_e32 v218, v219, v218
	v_max_f32_e32 v219, v79, v79
	v_max_f32_e32 v220, v127, v127
	v_max_f32_e32 v219, v220, v219
	v_max3_f32 v217, v217, v218, v219
	v_max_f32_e32 v218, v81, v81
	v_max_f32_e32 v219, v97, v97
	v_max_f32_e32 v218, v219, v218
	v_max_f32_e32 v219, v82, v82
	v_max_f32_e32 v220, v98, v98
	v_max_f32_e32 v219, v220, v219
	v_max_f32_e32 v220, v83, v83
	v_max_f32_e32 v221, v99, v99
	v_max3_f32 v218, v96, v80, v218
	v_max_f32_e32 v220, v221, v220
	v_max3_f32 v218, v218, v219, v220
	v_max_f32_e32 v219, v84, v84
	v_max_f32_e32 v220, v100, v100
	v_max_f32_e32 v219, v220, v219
	v_max_f32_e32 v220, v85, v85
	v_max_f32_e32 v221, v101, v101
	v_max_f32_e32 v220, v221, v220
	v_max3_f32 v218, v218, v219, v220
	v_max_f32_e32 v219, v86, v86
	v_max_f32_e32 v220, v102, v102
	v_max_f32_e32 v219, v220, v219
	v_max_f32_e32 v220, v87, v87
	v_max_f32_e32 v221, v103, v103
	v_max_f32_e32 v220, v221, v220
	v_max3_f32 v218, v218, v219, v220
	v_max_f32_e32 v219, v88, v88
	v_max_f32_e32 v220, v104, v104
	v_max_f32_e32 v219, v220, v219
	v_max_f32_e32 v220, v89, v89
	v_max_f32_e32 v221, v105, v105
	v_max_f32_e32 v220, v221, v220
	v_max3_f32 v218, v218, v219, v220
	v_max_f32_e32 v219, v90, v90
	v_max_f32_e32 v220, v106, v106
	v_max_f32_e32 v219, v220, v219
	v_max_f32_e32 v220, v91, v91
	v_max_f32_e32 v221, v107, v107
	v_max_f32_e32 v220, v221, v220
	v_max3_f32 v218, v218, v219, v220
	v_max_f32_e32 v219, v92, v92
	v_max_f32_e32 v220, v108, v108
	v_max_f32_e32 v219, v220, v219
	v_max_f32_e32 v220, v93, v93
	v_max_f32_e32 v221, v109, v109
	v_max_f32_e32 v220, v221, v220
	v_max3_f32 v218, v218, v219, v220
	v_max_f32_e32 v219, v94, v94
	v_max_f32_e32 v220, v110, v110
	v_max_f32_e32 v219, v220, v219
	v_max_f32_e32 v220, v95, v95
	v_max_f32_e32 v221, v111, v111
	v_max_f32_e32 v220, v221, v220
	ds_bpermute_b32 v221, v240, v217
	v_max3_f32 v219, v218, v219, v220
	ds_bpermute_b32 v220, v240, v219
	s_mov_b32 s2, 0x40c00000
	s_waitcnt lgkmcnt(1)
	v_max_f32_e32 v218, v221, v221
	v_max_f32_e32 v218, v217, v218
	s_waitcnt lgkmcnt(0)
	v_max_f32_e32 v217, v220, v220
	v_max_f32_e32 v217, v219, v217
	v_max_f32_e32 v219, v218, v217
	v_cmp_lt_f32_e32 vcc, s2, v219
	s_cmp_eq_u32 s28, 0
	s_cbranch_scc1 .Lat_resc
	s_cbranch_vccz .Lat_noresc
; DI void attn_unit(LAS unsigned char* lds, const bf16_t* Q, const bf16_t* Kn, const bf16_t* Kpe, const bf16_t* Vt, bf16_t* O, int b, int h, int qb) {
;     ...
;         if (kt == 0 || __builtin_amdgcn_ballot_w64(fmaxf(mx[0], mx[1]) > 6.0f) != 0ull) {
; #pragma unroll
;             for (int j = 0; j < 2; ++j) {
;                 const float dlt = kt == 0 ? mx[j] : fmaxf(mx[j], 0.f), alpha = __builtin_amdgcn_exp2f(-dlt);
;                 mrun[j] += dlt; lsum[j] *= alpha;
; #pragma unroll
;                 for (int i = 0; i < 16; ++i) { s[j][0][i] -= dlt; s[j][1][i] -= dlt; o[j][0][i] *= alpha; o[j][1][i] *= alpha; }
;             }
;         }
.Lat_resc:
	v_max_f32_e32 v218, v218, v218
	v_max_f32_e32 v218, s100, v218
	v_max_f32_e32 v217, v217, v217
	v_exp_f32_e64 v220, -v218
	v_max_f32_e32 v222, s100, v217
	v_exp_f32_e64 v224, -v222
	v_mov_b32_e32 v223, v218
	v_mov_b32_e32 v225, v220
	v_pk_add_f32 v[112:113], v[112:113], v[218:219] op_sel_hi:[1,0] neg_lo:[0,1] neg_hi:[0,1]
	v_pk_add_f32 v[64:65], v[64:65], v[218:219] op_sel_hi:[1,0] neg_lo:[0,1] neg_hi:[0,1]
	v_pk_add_f32 v[114:115], v[114:115], v[218:219] op_sel_hi:[1,0] neg_lo:[0,1] neg_hi:[0,1]
	v_pk_add_f32 v[66:67], v[66:67], v[218:219] op_sel_hi:[1,0] neg_lo:[0,1] neg_hi:[0,1]
	v_pk_add_f32 v[116:117], v[116:117], v[218:219] op_sel_hi:[1,0] neg_lo:[0,1] neg_hi:[0,1]
	v_pk_add_f32 v[68:69], v[68:69], v[218:219] op_sel_hi:[1,0] neg_lo:[0,1] neg_hi:[0,1]
	v_pk_add_f32 v[118:119], v[118:119], v[218:219] op_sel_hi:[1,0] neg_lo:[0,1] neg_hi:[0,1]
	v_pk_add_f32 v[70:71], v[70:71], v[218:219] op_sel_hi:[1,0] neg_lo:[0,1] neg_hi:[0,1]
	v_pk_add_f32 v[120:121], v[120:121], v[218:219] op_sel_hi:[1,0] neg_lo:[0,1] neg_hi:[0,1]
	v_pk_add_f32 v[72:73], v[72:73], v[218:219] op_sel_hi:[1,0] neg_lo:[0,1] neg_hi:[0,1]
	v_pk_add_f32 v[122:123], v[122:123], v[218:219] op_sel_hi:[1,0] neg_lo:[0,1] neg_hi:[0,1]
	v_pk_add_f32 v[74:75], v[74:75], v[218:219] op_sel_hi:[1,0] neg_lo:[0,1] neg_hi:[0,1]
	v_pk_add_f32 v[124:125], v[124:125], v[218:219] op_sel_hi:[1,0] neg_lo:[0,1] neg_hi:[0,1]
	v_pk_add_f32 v[76:77], v[76:77], v[218:219] op_sel_hi:[1,0] neg_lo:[0,1] neg_hi:[0,1]
	v_pk_add_f32 v[126:127], v[126:127], v[218:219] op_sel_hi:[1,0] neg_lo:[0,1] neg_hi:[0,1]
	v_pk_add_f32 v[78:79], v[78:79], v[218:219] op_sel_hi:[1,0] neg_lo:[0,1] neg_hi:[0,1]
	v_pk_mul_f32 v[62:63], v[62:63], v[220:221] op_sel_hi:[1,0]
	v_pk_mul_f32 v[60:61], v[60:61], v[220:221] op_sel_hi:[1,0]
	v_pk_mul_f32 v[58:59], v[58:59], v[220:221] op_sel_hi:[1,0]
	v_pk_mul_f32 v[56:57], v[56:57], v[220:221] op_sel_hi:[1,0]
	v_pk_mul_f32 v[54:55], v[54:55], v[220:221] op_sel_hi:[1,0]
	v_pk_mul_f32 v[52:53], v[52:53], v[220:221] op_sel_hi:[1,0]
	v_pk_mul_f32 v[50:51], v[50:51], v[220:221] op_sel_hi:[1,0]
	v_pk_mul_f32 v[48:49], v[48:49], v[220:221] op_sel_hi:[1,0]
	v_pk_mul_f32 v[30:31], v[30:31], v[220:221] op_sel_hi:[1,0]
	v_pk_mul_f32 v[28:29], v[28:29], v[220:221] op_sel_hi:[1,0]
	v_pk_mul_f32 v[26:27], v[26:27], v[220:221] op_sel_hi:[1,0]
	v_pk_mul_f32 v[24:25], v[24:25], v[220:221] op_sel_hi:[1,0]
	v_pk_mul_f32 v[22:23], v[22:23], v[220:221] op_sel_hi:[1,0]
	v_pk_mul_f32 v[20:21], v[20:21], v[220:221] op_sel_hi:[1,0]
	v_pk_mul_f32 v[18:19], v[18:19], v[220:221] op_sel_hi:[1,0]
	v_pk_mul_f32 v[16:17], v[16:17], v[220:221] op_sel_hi:[1,0]
	v_pk_add_f32 v[214:215], v[214:215], v[222:223]
	v_pk_mul_f32 v[212:213], v[212:213], v[224:225]
	v_pk_add_f32 v[96:97], v[96:97], v[222:223] op_sel_hi:[1,0] neg_lo:[0,1] neg_hi:[0,1]
	v_pk_add_f32 v[80:81], v[80:81], v[222:223] op_sel_hi:[1,0] neg_lo:[0,1] neg_hi:[0,1]
	v_pk_add_f32 v[98:99], v[98:99], v[222:223] op_sel_hi:[1,0] neg_lo:[0,1] neg_hi:[0,1]
	v_pk_add_f32 v[82:83], v[82:83], v[222:223] op_sel_hi:[1,0] neg_lo:[0,1] neg_hi:[0,1]
	v_pk_add_f32 v[100:101], v[100:101], v[222:223] op_sel_hi:[1,0] neg_lo:[0,1] neg_hi:[0,1]
	v_pk_add_f32 v[84:85], v[84:85], v[222:223] op_sel_hi:[1,0] neg_lo:[0,1] neg_hi:[0,1]
	v_pk_add_f32 v[102:103], v[102:103], v[222:223] op_sel_hi:[1,0] neg_lo:[0,1] neg_hi:[0,1]
	v_pk_add_f32 v[86:87], v[86:87], v[222:223] op_sel_hi:[1,0] neg_lo:[0,1] neg_hi:[0,1]
	v_pk_add_f32 v[104:105], v[104:105], v[222:223] op_sel_hi:[1,0] neg_lo:[0,1] neg_hi:[0,1]
	v_pk_add_f32 v[88:89], v[88:89], v[222:223] op_sel_hi:[1,0] neg_lo:[0,1] neg_hi:[0,1]
	v_pk_add_f32 v[106:107], v[106:107], v[222:223] op_sel_hi:[1,0] neg_lo:[0,1] neg_hi:[0,1]
	v_pk_add_f32 v[90:91], v[90:91], v[222:223] op_sel_hi:[1,0] neg_lo:[0,1] neg_hi:[0,1]
	v_pk_add_f32 v[108:109], v[108:109], v[222:223] op_sel_hi:[1,0] neg_lo:[0,1] neg_hi:[0,1]
	v_pk_add_f32 v[92:93], v[92:93], v[222:223] op_sel_hi:[1,0] neg_lo:[0,1] neg_hi:[0,1]
	v_pk_add_f32 v[110:111], v[110:111], v[222:223] op_sel_hi:[1,0] neg_lo:[0,1] neg_hi:[0,1]
	v_pk_add_f32 v[94:95], v[94:95], v[222:223] op_sel_hi:[1,0] neg_lo:[0,1] neg_hi:[0,1]
	v_pk_mul_f32 v[46:47], v[46:47], v[224:225] op_sel_hi:[1,0]
	v_pk_mul_f32 v[44:45], v[44:45], v[224:225] op_sel_hi:[1,0]
	v_pk_mul_f32 v[42:43], v[42:43], v[224:225] op_sel_hi:[1,0]
	v_pk_mul_f32 v[40:41], v[40:41], v[224:225] op_sel_hi:[1,0]
	v_pk_mul_f32 v[38:39], v[38:39], v[224:225] op_sel_hi:[1,0]
	v_pk_mul_f32 v[36:37], v[36:37], v[224:225] op_sel_hi:[1,0]
	v_pk_mul_f32 v[34:35], v[34:35], v[224:225] op_sel_hi:[1,0]
	v_pk_mul_f32 v[32:33], v[32:33], v[224:225] op_sel_hi:[1,0]
	v_pk_mul_f32 v[14:15], v[14:15], v[224:225] op_sel_hi:[1,0]
	v_pk_mul_f32 v[12:13], v[12:13], v[224:225] op_sel_hi:[1,0]
	v_pk_mul_f32 v[10:11], v[10:11], v[224:225] op_sel_hi:[1,0]
	v_pk_mul_f32 v[8:9], v[8:9], v[224:225] op_sel_hi:[1,0]
	v_pk_mul_f32 v[6:7], v[6:7], v[224:225] op_sel_hi:[1,0]
	v_pk_mul_f32 v[4:5], v[4:5], v[224:225] op_sel_hi:[1,0]
	v_pk_mul_f32 v[2:3], v[2:3], v[224:225] op_sel_hi:[1,0]
	v_pk_mul_f32 v[0:1], v[0:1], v[224:225] op_sel_hi:[1,0]

; #define LAS __attribute__((address_space(3)))
; DI void attn_unit(LAS unsigned char* lds, const bf16_t* Q, const bf16_t* Kn, const bf16_t* Kpe, const bf16_t* Vt, bf16_t* O, int b, int h, int qb) {
;     ...
; #pragma unroll
;         for (int j = 0; j < 2; ++j) {
;             float ps = 0.f;
; #pragma unroll
;             for (int i = 0; i < 16; ++i) { s[j][0][i] = __builtin_amdgcn_exp2f(s[j][0][i]); s[j][1][i] = __builtin_amdgcn_exp2f(s[j][1][i]); ps += s[j][0][i] + s[j][1][i]; }
;             lsum[j] += ps;
;         }
;         if (wid < 4) __builtin_amdgcn_s_setprio(3); else __builtin_amdgcn_s_setprio(1);
; #pragma unroll
;         for (int kbk = 0; kbk < 2; ++kbk) {
; #pragma unroll
;             for (int t = 0; t < 2; ++t) {
;                 const int koff = (32 * kbk + 16 * t + 4 * hi) * 2;
;                 const s16x4 a0l = *(const LAS s16x4*)(vb + r32 * VPITCH + koff), a0h = *(const LAS s16x4*)(vb + r32 * VPITCH + koff + 16);
;                 const s16x4 a1l = *(const LAS s16x4*)(vb + (32 + r32) * VPITCH + koff), a1h = *(const LAS s16x4*)(vb + (32 + r32) * VPITCH + koff + 16);
;                 const bf16x8 va0 = __builtin_shufflevector(a0l, a0h, 0, 1, 2, 3, 4, 5, 6, 7), va1 = __builtin_shufflevector(a1l, a1h, 0, 1, 2, 3, 4, 5, 6, 7);
; #pragma unroll
;                 for (int j = 0; j < 2; ++j) {
;                     u32x4 pw;
;                     pw.x = pk2(s[j][kbk][8 * t], s[j][kbk][8 * t + 1]); pw.y = pk2(s[j][kbk][8 * t + 2], s[j][kbk][8 * t + 3]);
;                     pw.z = pk2(s[j][kbk][8 * t + 4], s[j][kbk][8 * t + 5]); pw.w = pk2(s[j][kbk][8 * t + 6], s[j][kbk][8 * t + 7]);
;                     const bf16x8 pb = __builtin_bit_cast(bf16x8, pw);
;                     o[j][0] = __builtin_amdgcn_mfma_f32_32x32x16_bf16(va0, pb, o[j][0], 0, 0, 0);
;                     o[j][1] = __builtin_amdgcn_mfma_f32_32x32x16_bf16(va1, pb, o[j][1], 0, 0, 0);
;                 }
;             }
;         }
;         __builtin_amdgcn_s_setprio(0);
;         if (kt + 1 < 64) {
;             LAS unsigned char* kn2 = Ks + (buf ^ 1) * KBUF; LAS unsigned char* vn2 = Vs + (buf ^ 1) * VBUF;
;             *(LAS u32x4*)(kn2 + kn_l) = rk; if (tid < 256) *(LAS u32x4*)(kn2 + kp_l) = rp;
;             *(LAS u32x2*)(vn2 + vt_l) = (u32x2){rv.x, rv.y}; *(LAS u32x2*)(vn2 + vt_l + 8) = (u32x2){rv.z, rv.w};
;         }
.Lat_pv:
	s_mul_i32 s2, s30, 0x2200
	v_exp_f32_e32 v221, v112
	v_add_u32_e32 v112, s2, v241
	v_add_u32_e32 v217, 0x6800, v112
	v_add_u32_e32 v248, 0x7800, v112
	ds_read2_b64 v[228:231], v217 offset1:2
	ds_read2_b64 v[244:247], v248 offset0:32 offset1:34
	v_exp_f32_e32 v223, v113
	v_exp_f32_e32 v219, v114
	v_exp_f32_e32 v115, v115
	v_exp_f32_e32 v113, v116
	v_exp_f32_e32 v227, v117
	v_exp_f32_e32 v225, v118
	v_exp_f32_e32 v117, v119
	v_exp_f32_e32 v220, v96
	v_exp_f32_e32 v222, v97
	v_exp_f32_e32 v218, v98
	v_exp_f32_e32 v114, v99
	v_exp_f32_e32 v112, v100
	v_exp_f32_e32 v226, v101
	v_exp_f32_e32 v224, v102
	v_exp_f32_e32 v116, v103
	v_cvt_pk_bf16_f32 v234, v221, v223
	v_cvt_pk_bf16_f32 v235, v219, v115
	v_cvt_pk_bf16_f32 v236, v113, v227
	v_cvt_pk_bf16_f32 v237, v225, v117
	v_cvt_pk_bf16_f32 v96, v220, v222
	v_cvt_pk_bf16_f32 v97, v218, v114
	v_cvt_pk_bf16_f32 v98, v112, v226
	v_cvt_pk_bf16_f32 v99, v224, v116
	s_waitcnt lgkmcnt(1)
	v_mfma_f32_32x32x16_bf16 v[48:63], v[228:231], v[234:237], v[48:63]
	v_exp_f32_e32 v119, v123
	v_exp_f32_e32 v101, v124
	v_exp_f32_e32 v103, v125
	v_exp_f32_e32 v118, v107
	v_exp_f32_e32 v100, v108
	v_exp_f32_e32 v102, v109
	v_cvt_pk_bf16_f32 v124, v101, v103
	s_waitcnt lgkmcnt(0)
	v_mfma_f32_32x32x16_bf16 v[16:31], v[244:247], v[234:237], v[16:31]
	ds_read2_b64 v[234:237], v217 offset0:4 offset1:6
	v_exp_f32_e32 v109, v66
	v_exp_f32_e32 v107, v67
	v_exp_f32_e32 v69, v69
	v_exp_f32_e32 v67, v70
	v_exp_f32_e32 v108, v82
	v_exp_f32_e32 v66, v86
	v_mfma_f32_32x32x16_bf16 v[0:15], v[244:247], v[96:99], v[0:15]
	ds_read2_b64 v[244:247], v248 offset0:36 offset1:38
	v_exp_f32_e32 v77, v77
	v_exp_f32_e32 v86, v88
	v_exp_f32_e32 v82, v90
	v_exp_f32_e32 v70, v95
	v_mfma_f32_32x32x16_bf16 v[32:47], v[228:231], v[96:99], v[32:47]
	v_exp_f32_e32 v231, v120
	v_exp_f32_e32 v229, v121
	v_exp_f32_e32 v121, v122
	v_exp_f32_e32 v99, v126
	v_exp_f32_e32 v97, v127
	v_exp_f32_e32 v230, v104
	v_exp_f32_e32 v228, v105
	v_exp_f32_e32 v120, v106
	v_exp_f32_e32 v98, v110
	v_exp_f32_e32 v96, v111
	v_cvt_pk_bf16_f32 v122, v231, v229
	v_cvt_pk_bf16_f32 v123, v121, v119
	v_cvt_pk_bf16_f32 v125, v99, v97
	v_cvt_pk_bf16_f32 v126, v100, v102
	v_cvt_pk_bf16_f32 v127, v98, v96
	s_waitcnt lgkmcnt(1)
	v_mfma_f32_32x32x16_bf16 v[48:63], v[234:237], v[122:125], v[48:63]
	v_exp_f32_e32 v111, v65
	v_exp_f32_e32 v105, v68
	v_exp_f32_e32 v65, v71
	v_exp_f32_e32 v110, v81
	v_exp_f32_e32 v106, v83
	v_exp_f32_e32 v104, v84
	v_exp_f32_e32 v68, v85
	s_waitcnt lgkmcnt(0)
	v_mfma_f32_32x32x16_bf16 v[16:31], v[244:247], v[122:125], v[16:31]
	v_cvt_pk_bf16_f32 v124, v230, v228
	v_cvt_pk_bf16_f32 v125, v120, v118
	v_exp_f32_e32 v123, v64
	v_exp_f32_e32 v122, v80
	v_exp_f32_e32 v64, v87
	v_exp_f32_e32 v87, v72
	v_exp_f32_e32 v85, v73
	v_mfma_f32_32x32x16_bf16 v[32:47], v[234:237], v[124:127], v[32:47]
	ds_read2_b64 v[234:237], v217 offset0:8 offset1:10
	v_exp_f32_e32 v83, v74
	v_exp_f32_e32 v81, v75
	v_exp_f32_e32 v75, v76
	v_exp_f32_e32 v73, v78
	v_exp_f32_e32 v71, v79
	v_exp_f32_e32 v84, v89
	v_mfma_f32_32x32x16_bf16 v[0:15], v[244:247], v[124:127], v[0:15]
	ds_read2_b64 v[244:247], v248 offset0:40 offset1:42
	v_cvt_pk_bf16_f32 v124, v123, v111
	v_cvt_pk_bf16_f32 v125, v109, v107
	v_cvt_pk_bf16_f32 v126, v105, v69
	v_cvt_pk_bf16_f32 v127, v67, v65
	v_exp_f32_e32 v80, v91
	v_exp_f32_e32 v74, v92
	s_waitcnt lgkmcnt(1)
	v_mfma_f32_32x32x16_bf16 v[48:63], v[234:237], v[124:127], v[48:63]
	v_exp_f32_e32 v76, v93
	v_exp_f32_e32 v72, v94
	v_cvt_pk_bf16_f32 v88, v86, v84
	v_cvt_pk_bf16_f32 v89, v82, v80
	v_cvt_pk_bf16_f32 v90, v74, v76
	v_cvt_pk_bf16_f32 v91, v72, v70
	s_waitcnt lgkmcnt(0)
	v_mfma_f32_32x32x16_bf16 v[16:31], v[244:247], v[124:127], v[16:31]
	v_cvt_pk_bf16_f32 v124, v122, v110
	v_cvt_pk_bf16_f32 v125, v108, v106
	v_cvt_pk_bf16_f32 v126, v104, v68
	v_cvt_pk_bf16_f32 v127, v66, v64
	s_nop 1
	v_mfma_f32_32x32x16_bf16 v[32:47], v[234:237], v[124:127], v[32:47]
	ds_read2_b64 v[234:237], v217 offset0:12 offset1:14
	v_mfma_f32_32x32x16_bf16 v[0:15], v[244:247], v[124:127], v[0:15]
	ds_read2_b64 v[244:247], v248 offset0:44 offset1:46
	v_cvt_pk_bf16_f32 v124, v87, v85
	v_cvt_pk_bf16_f32 v125, v83, v81
	v_cvt_pk_bf16_f32 v126, v75, v77
	v_cvt_pk_bf16_f32 v127, v73, v71
	s_waitcnt lgkmcnt(1)
	s_nop 0
	v_mfma_f32_32x32x16_bf16 v[48:63], v[234:237], v[124:127], v[48:63]
	s_waitcnt lgkmcnt(0)
	v_mfma_f32_32x32x16_bf16 v[16:31], v[244:247], v[124:127], v[16:31]
	v_mfma_f32_32x32x16_bf16 v[32:47], v[234:237], v[88:91], v[32:47]
	v_mfma_f32_32x32x16_bf16 v[0:15], v[244:247], v[88:91], v[0:15]
	s_setprio 0
	s_andn2_b64 vcc, exec, s[16:17]
	s_cbranch_vccnz .Lat_tail
	s_and_b64 vcc, exec, s[26:27]
	s_cbranch_vccnz .Lat_tail
	s_xor_b32 s2, s30, 1
	s_mul_i32 s6, s2, 0x3400
	v_add_u32_e32 v78, s6, v210
	s_waitcnt vmcnt(1)
	ds_write_b128 v78, v[180:183]
	v_add_u32_e32 v78, s6, v242
	s_waitcnt vmcnt(0)
	ds_write_b128 v78, v[176:179] offset:128
	s_mulk_i32 s2, 0x2200
	v_add_u32_e32 v78, s2, v211
	v_add_u32_e32 v78, 0x6800, v78
	ds_write2_b64 v78, v[184:185], v[186:187] offset1:1
; #define LAS __attribute__((address_space(3)))
; DI void attn_unit(LAS unsigned char* lds, const bf16_t* Q, const bf16_t* Kn, const bf16_t* Kpe, const bf16_t* Vt, bf16_t* O, int b, int h, int qb) {
;     ...
;         for (int j = 0; j < 2; ++j) {
;             float ps = 0.f;
; #pragma unroll
;             for (int i = 0; i < 16; ++i) { s[j][0][i] = __builtin_amdgcn_exp2f(s[j][0][i]); s[j][1][i] = __builtin_amdgcn_exp2f(s[j][1][i]); ps += s[j][0][i] + s[j][1][i]; }
;             lsum[j] += ps;
;         }
;         if (wid < 4) __builtin_amdgcn_s_setprio(3); else __builtin_amdgcn_s_setprio(1);
; #pragma unroll
;         for (int kbk = 0; kbk < 2; ++kbk) {
; #pragma unroll
;             for (int t = 0; t < 2; ++t) {
;                 const int koff = (32 * kbk + 16 * t + 4 * hi) * 2;
;                 const s16x4 a0l = *(const LAS s16x4*)(vb + r32 * VPITCH + koff), a0h = *(const LAS s16x4*)(vb + r32 * VPITCH + koff + 16);
;                 const s16x4 a1l = *(const LAS s16x4*)(vb + (32 + r32) * VPITCH + koff), a1h = *(const LAS s16x4*)(vb + (32 + r32) * VPITCH + koff + 16);
;                 const bf16x8 va0 = __builtin_shufflevector(a0l, a0h, 0, 1, 2, 3, 4, 5, 6, 7), va1 = __builtin_shufflevector(a1l, a1h, 0, 1, 2, 3, 4, 5, 6, 7);
; #pragma unroll
;                 for (int j = 0; j < 2; ++j) {
;                     u32x4 pw;
;                     pw.x = pk2(s[j][kbk][8 * t], s[j][kbk][8 * t + 1]); pw.y = pk2(s[j][kbk][8 * t + 2], s[j][kbk][8 * t + 3]);
;                     pw.z = pk2(s[j][kbk][8 * t + 4], s[j][kbk][8 * t + 5]); pw.w = pk2(s[j][kbk][8 * t + 6], s[j][kbk][8 * t + 7]);
;                     const bf16x8 pb = __builtin_bit_cast(bf16x8, pw);
;                     o[j][0] = __builtin_amdgcn_mfma_f32_32x32x16_bf16(va0, pb, o[j][0], 0, 0, 0);
;                     o[j][1] = __builtin_amdgcn_mfma_f32_32x32x16_bf16(va1, pb, o[j][1], 0, 0, 0);
;                 }
;             }
;         }
;         __builtin_amdgcn_s_setprio(0);
;         if (kt + 1 < 64) {
;             LAS unsigned char* kn2 = Ks + (buf ^ 1) * KBUF; LAS unsigned char* vn2 = Vs + (buf ^ 1) * VBUF;
;             *(LAS u32x4*)(kn2 + kn_l) = rk; if (tid < 256) *(LAS u32x4*)(kn2 + kp_l) = rp;
;             *(LAS u32x2*)(vn2 + vt_l) = (u32x2){rv.x, rv.y}; *(LAS u32x2*)(vn2 + vt_l + 8) = (u32x2){rv.z, rv.w};
;         }
;         __syncthreads();
;     }
.Lat_tail:
	s_mov_b32 s100, 0
	v_add_f32_e32 v78, v122, v220
	v_add_f32_e32 v79, v123, v221
	v_add_f32_e32 v88, v110, v222
	v_add_f32_e32 v89, v111, v223
	v_add_f32_e32 v68, v68, v226
	v_add_f32_e32 v69, v69, v227
	v_add_f32_e32 v78, v88, v78
	v_add_f32_e32 v79, v89, v79
	v_add_f32_e32 v88, v108, v218
	v_add_f32_e32 v89, v109, v219
	v_add_f32_e32 v66, v66, v224
	v_add_f32_e32 v67, v67, v225
	v_add_f32_e32 v78, v88, v78
	v_add_f32_e32 v79, v89, v79
	v_add_f32_e32 v88, v106, v114
	v_add_f32_e32 v89, v107, v115
	v_add_f32_e32 v64, v64, v116
	v_add_f32_e32 v65, v65, v117
	v_add_f32_e32 v78, v88, v78
	v_add_f32_e32 v79, v89, v79
	v_add_f32_e32 v88, v104, v112
	v_add_f32_e32 v89, v105, v113
	s_addk_i32 s29, 0x800
	v_add_f32_e32 v78, v88, v78
	v_add_f32_e32 v79, v89, v79
	s_add_i32 s28, s28, 1
	v_add_f32_e32 v68, v68, v78
	v_add_f32_e32 v69, v69, v79
	v_add_u32_e32 v216, 64, v216
	v_add_f32_e32 v66, v66, v68
	v_add_f32_e32 v67, v67, v69
	s_cmp_lg_u32 s29, 0x1f800
	v_add_f32_e32 v64, v64, v66
	v_add_f32_e32 v65, v65, v67
	v_add_f32_e32 v66, v86, v230
	v_add_f32_e32 v67, v87, v231
	v_add_u32_e32 v188, 0x1000, v188
	v_add_f32_e32 v64, v66, v64
	v_add_f32_e32 v65, v67, v65
	v_add_f32_e32 v66, v84, v228
	v_add_f32_e32 v67, v85, v229
	s_waitcnt lgkmcnt(0)
	v_add_f32_e32 v64, v66, v64
	v_add_f32_e32 v65, v67, v65
	v_add_f32_e32 v66, v82, v120
	v_add_f32_e32 v67, v83, v121
	s_barrier
	v_add_f32_e32 v64, v66, v64
	v_add_f32_e32 v65, v67, v65
	v_add_f32_e32 v66, v80, v118
	v_add_f32_e32 v67, v81, v119
	v_add_f32_e32 v64, v66, v64
	v_add_f32_e32 v65, v67, v65
	v_add_f32_e32 v66, v74, v100
	v_add_f32_e32 v67, v75, v101
	v_add_f32_e32 v64, v66, v64
	v_add_f32_e32 v65, v67, v65
	v_add_f32_e32 v66, v76, v102
	v_add_f32_e32 v67, v77, v103
	v_add_f32_e32 v64, v66, v64
	v_add_f32_e32 v65, v67, v65
	v_add_f32_e32 v66, v72, v98
	v_add_f32_e32 v67, v73, v99
	v_add_f32_e32 v64, v66, v64
	v_add_f32_e32 v65, v67, v65
	v_add_f32_e32 v66, v70, v96
	v_add_f32_e32 v67, v71, v97
	v_add_f32_e32 v64, v66, v64
	v_add_f32_e32 v65, v67, v65
	v_add_f32_e32 v212, v212, v64
	v_add_f32_e32 v213, v213, v65
	s_cbranch_scc1 .Lat_loop
	s_and_b64 vcc, exec, s[26:27]
	s_cbranch_vccnz .LBB0_1104
	s_barrier
	s_branch .LBB0_1104

; __global__ void __launch_bounds__(512, 2) mega(Params P) {
;     extern __shared__ __attribute__((aligned(16))) unsigned char smem_raw[];
	.amdhsa_kernel _Z4mega6Params
		.amdhsa_group_segment_fixed_size 0
		.amdhsa_private_segment_fixed_size 0
		.amdhsa_kernarg_size 472
		.amdhsa_user_sgpr_count 2
		.amdhsa_user_sgpr_dispatch_ptr 0
		.amdhsa_user_sgpr_queue_ptr 0
		.amdhsa_user_sgpr_kernarg_segment_ptr 1
		.amdhsa_user_sgpr_dispatch_id 0
		.amdhsa_user_sgpr_kernarg_preload_length 0
		.amdhsa_user_sgpr_kernarg_preload_offset 0
		.amdhsa_user_sgpr_private_segment_size 0
		.amdhsa_uses_dynamic_stack 0
		.amdhsa_enable_private_segment 0
		.amdhsa_system_sgpr_workgroup_id_x 1
		.amdhsa_system_sgpr_workgroup_id_y 0
		.amdhsa_system_sgpr_workgroup_id_z 0
		.amdhsa_system_sgpr_workgroup_info 0
		.amdhsa_system_vgpr_workitem_id 2
		.amdhsa_next_free_vgpr 256
		.amdhsa_next_free_sgpr 102
		.amdhsa_accum_offset 256
		.amdhsa_reserve_vcc 1
		.amdhsa_float_round_mode_32 0
		.amdhsa_float_round_mode_16_64 0
		.amdhsa_float_denorm_mode_32 3
		.amdhsa_float_denorm_mode_16_64 3
		.amdhsa_dx10_clamp 1
		.amdhsa_ieee_mode 1
		.amdhsa_fp16_overflow 0
		.amdhsa_tg_split 0
		.amdhsa_exception_fp_ieee_invalid_op 0
		.amdhsa_exception_fp_denorm_src 0
		.amdhsa_exception_fp_ieee_div_zero 0
		.amdhsa_exception_fp_ieee_overflow 0
		.amdhsa_exception_fp_ieee_underflow 0
		.amdhsa_exception_fp_ieee_inexact 0
		.amdhsa_exception_int_div_zero 0
	.end_amdhsa_kernel

amdhsa.kernels:
  - .agpr_count:     0
    .args:
      - .offset:         0
        .size:           216
        .value_kind:     by_value
      - .offset:         216
        .size:           4
        .value_kind:     hidden_block_count_x
      - .offset:         220
        .size:           4
        .value_kind:     hidden_block_count_y
      - .offset:         224
        .size:           4
        .value_kind:     hidden_block_count_z
      - .offset:         228
        .size:           2
        .value_kind:     hidden_group_size_x
      - .offset:         230
        .size:           2
        .value_kind:     hidden_group_size_y
      - .offset:         232
        .size:           2
        .value_kind:     hidden_group_size_z
      - .offset:         234
        .size:           2
        .value_kind:     hidden_remainder_x
      - .offset:         236
        .size:           2
        .value_kind:     hidden_remainder_y
      - .offset:         238
        .size:           2
        .value_kind:     hidden_remainder_z
      - .offset:         256
        .size:           8
        .value_kind:     hidden_global_offset_x
      - .offset:         264
        .size:           8
        .value_kind:     hidden_global_offset_y
      - .offset:         272
        .size:           8
        .value_kind:     hidden_global_offset_z
      - .offset:         280
        .size:           2
        .value_kind:     hidden_grid_dims
      - .offset:         304
        .size:           8
        .value_kind:     hidden_multigrid_sync_arg
      - .offset:         336
        .size:           4
        .value_kind:     hidden_dynamic_lds_size
    .group_segment_fixed_size: 0
    .kernarg_segment_align: 8
    .kernarg_segment_size: 472
    .language:       OpenCL C
    .language_version:
      - 2
      - 0
    .max_flat_workgroup_size: 512
    .name:           _Z4mega6Params
    .private_segment_fixed_size: 0
    .sgpr_count:     108
    .sgpr_spill_count: 138
    .symbol:         _Z4mega6Params.kd
    .uniform_work_group_size: 1
    .uses_dynamic_stack: false
    .vgpr_count:     256
    .vgpr_spill_count: 0
    .wavefront_size: 64
